# retention: deferred weight-conversion loads issued after the K DMAs (post P-exchange barrier) and stored one tile later, so the tile-end vmcnt no longer waits on HBM loads
# baseline (speedup 1.0000x reference)
; #define RT_BAR() do { asm volatile("s_waitcnt lgkmcnt(0)" ::: "memory"); __builtin_amdgcn_s_barrier(); asm volatile("" ::: "memory"); } while (0)
; __device__ __forceinline__ void p2_ret(const Frame& F, ArgsP a, int layer) {
;     ...
;             const int qi = uu ? p : 15 - p, ntile = 2 * (qi + 1);
;             const size_t tokq = (size_t)b * SEQ + qi * 128;
;             f32x16 oacc[4];
; #pragma unroll
;             for (int db = 0; db < 4; ++db)
; #pragma unroll
;                 for (int r = 0; r < 16; ++r) oacc[db][r] = 0.f;
;             asm volatile("s_waitcnt vmcnt(0)" ::: "memory"); RT_BAR();
.LBB0_355:
	s_xor_b64 s[72:73], s[74:75], -1
	s_and_b64 s[2:3], s[74:75], exec
	s_waitcnt vmcnt(0)
	s_cselect_b32 s96, s89, s50
	s_waitcnt lgkmcnt(0)
	s_barrier
	s_mov_b32 s85, 0
	s_lshl_b32 s19, s96, 7
	s_lshl_b32 s11, s96, 8
	v_mov_b32_e32 v34, 0
	s_lshl_b32 s29, s96, 1
	s_add_i32 s97, s81, s19
	s_bitset1_b32 s11, 7
	s_mov_b32 s31, 0
	s_mov_b32 s27, s88
	s_mov_b32 s30, 0
	s_mov_b32 s91, 0
	v_mov_b32_e32 v35, v34
	v_mov_b32_e32 v36, v34
	v_mov_b32_e32 v37, v34
	v_mov_b32_e32 v38, v34
	v_mov_b32_e32 v39, v34
	v_mov_b32_e32 v40, v34
	v_mov_b32_e32 v41, v34
	v_mov_b32_e32 v42, v34
	v_mov_b32_e32 v43, v34
	v_mov_b32_e32 v44, v34
	v_mov_b32_e32 v45, v34
	v_mov_b32_e32 v46, v34
	v_mov_b32_e32 v47, v34
	v_mov_b32_e32 v48, v34
	v_mov_b32_e32 v49, v34
	v_mov_b32_e32 v50, v34
	v_mov_b32_e32 v51, v34
	v_mov_b32_e32 v52, v34
	v_mov_b32_e32 v53, v34
	v_mov_b32_e32 v54, v34
	v_mov_b32_e32 v55, v34
	v_mov_b32_e32 v56, v34
	v_mov_b32_e32 v57, v34
	v_mov_b32_e32 v58, v34
	v_mov_b32_e32 v59, v34
	v_mov_b32_e32 v60, v34
	v_mov_b32_e32 v61, v34
	v_mov_b32_e32 v62, v34
	v_mov_b32_e32 v63, v34
	v_mov_b32_e32 v64, v34
	v_mov_b32_e32 v65, v34
	v_mov_b32_e32 v66, v34
	v_mov_b32_e32 v67, v34
	v_mov_b32_e32 v68, v34
	v_mov_b32_e32 v69, v34
	v_mov_b32_e32 v70, v34
	v_mov_b32_e32 v71, v34
	v_mov_b32_e32 v72, v34
	v_mov_b32_e32 v73, v34
	v_mov_b32_e32 v74, v34
	v_mov_b32_e32 v75, v34
	v_mov_b32_e32 v76, v34
	v_mov_b32_e32 v77, v34
	v_mov_b32_e32 v78, v34
	v_mov_b32_e32 v79, v34
	v_mov_b32_e32 v80, v34
	v_mov_b32_e32 v81, v34
	v_mov_b32_e32 v82, v34
	v_mov_b32_e32 v83, v34
	v_mov_b32_e32 v84, v34
	v_mov_b32_e32 v85, v34
	v_mov_b32_e32 v86, v34
	v_mov_b32_e32 v87, v34
	v_mov_b32_e32 v88, v34
	v_mov_b32_e32 v89, v34
	v_mov_b32_e32 v90, v34
	v_mov_b32_e32 v91, v34
	v_mov_b32_e32 v92, v34
	v_mov_b32_e32 v93, v34
	v_mov_b32_e32 v94, v34
	v_mov_b32_e32 v95, v34
	v_mov_b32_e32 v96, v34
	v_mov_b32_e32 v97, v34
	s_branch .LBB0_358

; __device__ __forceinline__ CvU cv_decode(ArgsP a, unsigned char* ws, int hi, int layer) {
;     CvU u; int fi = hi >> 1; const int half = hi & 1; int l = layer, kind;
;     if (fi < CV_GLU) kind = 0; else if ((fi -= CV_GLU) < CV_OUT) kind = 1; else { fi -= CV_OUT; kind = 2; l = layer + 1; }
;     int kb, nb;
; __device__ __forceinline__ void p2_ret(const Frame& F, ArgsP a, int layer) {
;     ...
;                 const bool cv = cvhi < CV_HALF_ITEMS && ((cvtile++ & 1) == 0); f32x4 cvv[8], cvsc[2];
;                 if (cv) { const CvU cu = cv_decode(a, F.ws, cvhi, layer); cv_load(cu, lane, cvv, cvsc); }
.Lrk_skip:
	s_and_b64 vcc, exec, s[38:39]
	s_cbranch_vccnz .Lcvl_noload
	s_ashr_i32 s15, s36, 1
	s_cmpk_gt_i32 s15, 0x3ff
	s_cselect_b64 s[6:7], -1, 0
	s_cmpk_lt_i32 s15, 0x400
	s_mov_b64 s[70:71], 0
	s_cbranch_scc1 .LBB0_365
	s_mov_b64 s[4:5], -1
	s_cmpk_gt_u32 s15, 0x13ff
	s_mov_b64 s[12:13], -1
	s_cbranch_scc0 .LBB0_362
	s_add_i32 s14, s15, 0xffffec00
	s_mov_b64 s[12:13], 0

; #define RT_VRD(dst, g) do { _Pragma("unroll") for (int j_ = 0; j_ < 2; ++j_) { const int jj_ = 2 * ((g) & 1) + j_; dst[j_] = *(const LAS bf16x8*)(vb + ((g) >> 1) * 4096 + (((4 * (jj_ >> 1) + 2 * (jj_ & 1) + hh) << 4) ^ m4)); } } while (0)
; #define RT_VMM(src, g) do { _Pragma("unroll") for (int j_ = 0; j_ < 2; ++j_) { const int jj_ = 2 * ((g) & 1) + j_; oacc[(g) >> 1] = __builtin_amdgcn_mfma_f32_32x32x16_bf16(src[j_], pf[jj_ >> 1][jj_ & 1], oacc[(g) >> 1], 0, 0, 0); } } while (0)
; __device__ __forceinline__ void p2_ret(const Frame& F, ArgsP a, int layer) {
;     ...
;                 const bool cv = cvhi < CV_HALF_ITEMS && ((cvtile++ & 1) == 0); f32x4 cvv[8], cvsc[2];
;                 if (cv) { const CvU cu = cv_decode(a, F.ws, cvhi, layer); cv_load(cu, lane, cvv, cvsc); }
;     ...
;                   RT_VRD(vc, 1); RT_VMM(va, 0); __builtin_amdgcn_sched_barrier(0);
;                   RT_VRD(va, 2); RT_VMM(vc, 1); __builtin_amdgcn_sched_barrier(0);
;                   RT_VRD(vc, 3); RT_VMM(va, 2); __builtin_amdgcn_sched_barrier(0);
;                   RT_VRD(va, 4); RT_VMM(vc, 3); __builtin_amdgcn_sched_barrier(0);
;                   RT_VRD(vc, 5); RT_VMM(va, 4); __builtin_amdgcn_sched_barrier(0);
;                   RT_VRD(va, 6); RT_VMM(vc, 5); __builtin_amdgcn_sched_barrier(0);
;                   RT_VRD(vc, 7); RT_VMM(va, 6); __builtin_amdgcn_sched_barrier(0);
;                   RT_VMM(vc, 7); __builtin_amdgcn_sched_barrier(0);
;     ...
;                 }
;                 asm volatile("s_waitcnt vmcnt(0)" ::: "memory");
.Lcvl_loaded:
	s_mov_b32 s85, 2
.Lcvl_noload:
	s_waitcnt lgkmcnt(5)
	v_mfma_f32_32x32x16_bf16 v[34:49], v[242:245], v[190:193], v[34:49]
	s_waitcnt lgkmcnt(4)
	v_mfma_f32_32x32x16_bf16 v[34:49], v[106:109], v[194:197], v[34:49]
	ds_read_b128 v[242:245], v248 offset:4096
	ds_read_b128 v[106:109], v249 offset:4096
	s_waitcnt lgkmcnt(2)
	v_mfma_f32_32x32x16_bf16 v[82:97], v[234:237], v[98:101], v[82:97]
	v_mfma_f32_32x32x16_bf16 v[82:97], v[238:241], v[102:105], v[82:97]
	ds_read_b128 v[234:237], v248 offset:8192
	ds_read_b128 v[238:241], v249 offset:8192
	s_waitcnt lgkmcnt(3)
	v_mfma_f32_32x32x16_bf16 v[66:81], v[242:245], v[98:101], v[66:81]
	s_waitcnt lgkmcnt(2)
	v_mfma_f32_32x32x16_bf16 v[66:81], v[106:109], v[102:105], v[66:81]
	ds_read_b128 v[242:245], v248 offset:12288
	ds_read_b128 v[106:109], v249 offset:12288
	s_waitcnt lgkmcnt(3)
	v_mfma_f32_32x32x16_bf16 v[50:65], v[234:237], v[98:101], v[50:65]
	s_waitcnt lgkmcnt(2)
	v_mfma_f32_32x32x16_bf16 v[50:65], v[238:241], v[102:105], v[50:65]
	s_waitcnt lgkmcnt(1)
	v_mfma_f32_32x32x16_bf16 v[34:49], v[242:245], v[98:101], v[34:49]
	s_waitcnt lgkmcnt(0)
	v_mfma_f32_32x32x16_bf16 v[34:49], v[106:109], v[102:105], v[34:49]
	s_add_i32 s12, s30, 0x80
	s_cmp_eq_u32 s12, s11
	s_cbranch_scc1 .Lrk_w0
	s_cmp_eq_u32 s85, 2
	s_cbranch_scc1 .Lrk_wl
	s_waitcnt vmcnt(4)
	s_branch .Lrk_wd
.Lrk_wl:
	s_cmp_eq_u64 s[70:71], 0
	s_cbranch_scc1 .Lrk_w12
	s_waitcnt vmcnt(14)
	s_branch .Lrk_wd
.Lrk_w12:
	s_waitcnt vmcnt(12)
	s_branch .Lrk_wd

; #define RT_BAR() do { asm volatile("s_waitcnt lgkmcnt(0)" ::: "memory"); __builtin_amdgcn_s_barrier(); asm volatile("" ::: "memory"); } while (0)
; __device__ __forceinline__ CvU cv_decode(ArgsP a, unsigned char* ws, int hi, int layer) {
;     CvU u; int fi = hi >> 1; const int half = hi & 1; int l = layer, kind;
;     if (fi < CV_GLU) kind = 0; else if ((fi -= CV_GLU) < CV_OUT) kind = 1; else { fi -= CV_OUT; kind = 2; l = layer + 1; }
;     int kb, nb;
; __device__ __forceinline__ void p2_ret(const Frame& F, ArgsP a, int layer) {
;     ...
;                 asm volatile("s_waitcnt vmcnt(0)" ::: "memory");
;                 if (cv) { const CvU cu = cv_decode(a, F.ws, cvhi, layer); cv_store(cu, lane, cvv, cvsc); cvhi += cvs; }
;                 RT_BAR();
.Lrk_wd:
	s_cmp_eq_u32 s85, 0
	s_cbranch_scc1 .LBB0_357
	s_cmp_eq_u32 s85, 1
	s_cbranch_scc1 .Lcvl_store
	s_mov_b32 s85, 1
	s_add_i32 s12, s30, 0x80
	s_cmp_eq_u32 s12, s11
	s_cbranch_scc0 .LBB0_357
.Lcvl_store:
	s_mov_b32 s85, 0
	v_mov_b32_e32 v0, v207
	s_ashr_i32 s14, s36, 1
	s_cmpk_lt_i32 s14, 0x400
	s_cselect_b64 s[4:5], -1, 0
	s_mov_b64 s[70:71], 0
	s_and_b64 vcc, exec, s[4:5]
	s_cbranch_vccnz .LBB0_394
	s_mov_b64 s[46:47], -1
	s_cmpk_gt_u32 s14, 0x13ff
	s_mov_b64 s[6:7], -1
	s_cbranch_scc0 .LBB0_391
	s_add_i32 s12, s14, 0xffffec00
	s_mov_b64 s[6:7], 0
